# v15 plus: loop counter/ring rotation executed before the last barrier of the iteration (back edge right after the barrier)
# speedup vs baseline: 1.0204x; 1.0204x over previous
; #define AT_BAR() do { __builtin_amdgcn_sched_barrier(0); asm volatile("s_waitcnt lgkmcnt(0)\n\ts_barrier" ::: "memory"); __builtin_amdgcn_sched_barrier(0); } while (0)
; __device__ __forceinline__ void attn_phase(LAS unsigned char* lds, const bf16_t* Qb, const bf16_t* Kimg, const bf16_t* Vimg, bf16_t* AB, int bid, int G, int wave_k) {
;     ...
;         for (int t = 0; t < 256; ++t) {
;     ...
;             AT_BAR();
;             const int tmp = b_prev; b_prev = b_cur; b_cur = b_next; b_next = tmp;
.Lat_dma_done:
	s_add_i32 s61, s61, 1
	s_mov_b32 s16, s62
	s_mov_b32 s62, s63
	s_mov_b32 s63, s64
	s_mov_b32 s64, s16
	s_cmpk_lg_i32 s61, 0x100
.LBB0_981:
	s_barrier
	s_cbranch_scc1 .LBB0_963
	s_branch .LBB0_983
